# in-proj main GEMM: workgroups start the phase in four groups 1.5us apart (spreads the epilogue store bursts)
# speedup vs baseline: 1.0105x; 1.0105x over previous
.LBB0_689:
	v_readlane_b32 s2, v254, 36
	v_readlane_b32 s3, v254, 37
	s_mov_b32 s10, s2
	s_lshl_b32 s2, s2, 1
	s_ashr_i32 s3, s2, 31
	s_lshl_b64 s[2:3], s[2:3], 18
	s_waitcnt lgkmcnt(0)
	s_add_u32 s5, s78, s2
	s_addc_u32 s6, s79, s3
	v_readlane_b32 s2, v254, 38
	v_readlane_b32 s3, v254, 39
	s_lshl_b64 s[2:3], s[2:3], 3
	s_add_u32 s2, s5, s2
	s_addc_u32 s3, s6, s3
	s_ashr_i32 s11, s10, 31
	s_load_dword s8, s[84:85], 0x0
	s_lshl_b64 s[6:7], s[10:11], 24
	s_add_u32 s5, s78, s6
	s_addc_u32 s6, s79, s7
	s_add_u32 s11, s5, 0x200000
	s_addc_u32 s12, s6, 0
	s_andn2_b64 vcc, exec, s[0:1]
	s_cbranch_vccnz .LBB0_769
	v_ashrrev_i32_e32 v0, 31, v10
	v_lshrrev_b32_e32 v0, 26, v0
	v_add_u32_e32 v0, v10, v0
	v_ashrrev_i32_e32 v11, 6, v0
	v_bfe_i32 v0, v10, 27, 1
	v_lshlrev_b32_e32 v2, 4, v10
	v_lshrrev_b32_e32 v0, 22, v0
	v_add_u32_e32 v0, v2, v0
	v_and_b32_e32 v0, 0xfffffc00, v0
	v_sub_u32_e32 v0, v2, v0
	v_lshrrev_b32_e32 v3, 4, v0
	v_bitop3_b32 v3, v3, v0, 32 bitop3:0x6c
	v_ashrrev_i32_e32 v0, 31, v0
	v_lshrrev_b32_e32 v0, 26, v0
	v_add_u32_e32 v0, v3, v0
	v_ashrrev_i32_e32 v12, 6, v0
	v_lshlrev_b32_e32 v4, 3, v11
	v_mul_i32_i24_e32 v5, 64, v12
	v_and_b32_e32 v4, -16, v4
	v_sub_u32_e32 v3, v3, v5
	v_add_u32_e32 v0, v12, v4
	v_ashrrev_i16_sdwa v3, v209, sext(v3) dst_sel:DWORD dst_unused:UNUSED_PAD src0_sel:DWORD src1_sel:BYTE_0
	v_lshlrev_b32_e32 v4, 5, v11
	v_bfe_i32 v13, v3, 0, 16
	v_lshlrev_b32_e32 v3, 1, v0
	v_lshrrev_b32_e32 v5, 2, v0
	v_and_b32_e32 v6, 3, v12
	v_and_b32_e32 v4, 32, v4
	v_and_b32_e32 v3, 24, v3
	v_and_b32_e32 v5, 4, v5
	v_and_or_b32 v6, v0, s76, v6
	v_or3_b32 v3, v6, v5, v3
	v_add_lshl_u32 v4, v4, v13, 1
	v_add_u32_e32 v2, 0x2000, v2
	v_lshl_add_u32 v130, v0, 11, v4
	v_lshl_add_u32 v0, v3, 11, v4
	v_ashrrev_i32_e32 v3, 31, v2
	v_lshrrev_b32_e32 v3, 22, v3
	v_add_u32_e32 v3, v2, v3
	v_ashrrev_i32_e32 v14, 10, v3
	v_mul_i32_i24_e32 v3, 0x400, v14
	v_sub_u32_e32 v2, v2, v3
	v_lshrrev_b32_e32 v3, 4, v2
	v_bitop3_b32 v2, v3, v2, 32 bitop3:0x6c
	v_ashrrev_i32_e32 v4, 31, v2
	v_lshrrev_b32_e32 v4, 26, v4
	v_add_u32_e32 v4, v2, v4
	v_lshlrev_b32_e32 v3, 3, v14
	v_ashrrev_i32_e32 v15, 6, v4
	v_and_b32_e32 v4, 0xc0, v4
	s_ashr_i32 s19, s4, 6
	s_ashr_i32 s55, s54, 31
	s_ashr_i32 s43, s42, 31
	s_ashr_i32 s5, s4, 8
	v_and_b32_e32 v3, -16, v3
	v_sub_u32_e32 v2, v2, v4
	s_lshl_b32 s10, s19, 10
	s_lshl_b64 s[6:7], s[54:55], 19
	s_lshl_b64 s[0:1], s[42:43], 19
	v_add_u32_e32 v3, v15, v3
	v_ashrrev_i16_sdwa v2, v209, sext(v2) dst_sel:DWORD dst_unused:UNUSED_PAD src0_sel:DWORD src1_sel:BYTE_0
	s_add_u32 s0, s11, s0
	v_lshlrev_b32_e32 v5, 5, v14
	v_bfe_i32 v16, v2, 0, 16
	v_lshlrev_b32_e32 v2, 1, v3
	v_lshrrev_b32_e32 v4, 2, v3
	v_and_b32_e32 v6, 3, v15
	s_addc_u32 s1, s12, s1
	s_add_i32 s13, s10, 0
	v_and_b32_e32 v5, 32, v5
	v_and_b32_e32 v2, 24, v2
	v_and_b32_e32 v4, 4, v4
	v_and_or_b32 v6, v3, s76, v6
	s_bfe_u32 s98, s51, 0x20003
.Lstag_lp:
	s_cmp_eq_u32 s98, 0
	s_cbranch_scc1 .Lstag_inproj
	s_sleep 36
	s_sub_u32 s98, s98, 1
	s_branch .Lstag_lp
